# attention output store tails (sliding-window x3, MLA x2): v_permlane32_swap_b32 pairs turn eight 8-byte stores per lane into four dwordx4
# baseline (speedup 1.0000x reference)
; __device__ __forceinline__ unsigned cvtpk(float lo, float hi) { unsigned r; asm volatile("v_cvt_pk_bf16_f32 %0, %1, %2" : "=v"(r) : "v"(lo), "v"(hi)); return r; }
; __device__ __forceinline__ float shfl_x(float v, int m, int lane) { return __builtin_bit_cast(float, __builtin_amdgcn_ds_bpermute((lane ^ m) << 2, __builtin_bit_cast(int, v))); }
; __device__ __forceinline__ void swa_unit3(LAS unsigned char* lds, const bf16_t* pb  , bf16_t* Yb  , int q0, int kvh,
;                                           const float* sinks  , unsigned long long* gss, const int wave_s) {
;     ...
;         const float lt = l_run + shfl_x(l_run, 32, lane);
;         const float inv = 1.0f / lt;
;         bf16_t* orow = Yb + (size_t)(qw0 + r32) * DM + 64 * hq + 4 * hi;
; #pragma unroll
;         for (int rg = 0; rg < 4; ++rg) {
;             u32x2 a, b;
;             a.x = cvtpk(o0[4 * rg] * inv, o0[4 * rg + 1] * inv); a.y = cvtpk(o0[4 * rg + 2] * inv, o0[4 * rg + 3] * inv);
;             b.x = cvtpk(o1[4 * rg] * inv, o1[4 * rg + 1] * inv); b.y = cvtpk(o1[4 * rg + 2] * inv, o1[4 * rg + 3] * inv);
;             *(u32x2*)(orow + 8 * rg) = a; *(u32x2*)(orow + 32 + 8 * rg) = b;
;         }
;         { float q = 0.f;
; #pragma unroll
;           for (int r = 0; r < 16; ++r) { const float a = o0[r] * inv, b = o1[r] * inv; q += a * a + b * b; }
;           q += shfl_x(q, 32, lane);
;           if (hi == 0) __hip_atomic_fetch_add(gss + qw0 + r32, (unsigned long long)(q * 16777216.0f), __ATOMIC_RELAXED, __HIP_MEMORY_SCOPE_AGENT); }
.LBB0_804:
	s_ashr_i32 s13, s12, 31
	s_lshl_b32 s25, s2, 6
	s_lshl_b32 s24, s3, 6
	s_lshl_b64 s[2:3], s[12:13], 23
	s_add_u32 s2, s20, s2
	s_addc_u32 s3, s21, s3
	v_lshlrev_b64 v[2:3], 11, v[166:167]
	v_lshl_add_u64 v[2:3], s[2:3], 0, v[2:3]
	v_lshlrev_b32_e32 v0, 1, v168
	s_add_u32 s10, s18, s94
	v_lshl_add_u64 v[2:3], v[2:3], 0, v[0:1]
	ds_bpermute_b32 v0, v17, v173
	s_addc_u32 s11, s19, s95
	s_lshl_b64 s[8:9], s[12:13], 15
	s_add_u32 s10, s10, s8
	s_addc_u32 s11, s11, s9
	s_mov_b64 s[2:3], 0x2c800000
	s_ashr_i32 s17, s16, 31
	v_lshl_add_u64 v[152:153], v[2:3], 0, s[2:3]
	s_lshl_b64 s[2:3], s[16:17], 3
	s_add_u32 s2, s10, s2
	s_waitcnt lgkmcnt(0)
	v_add_f32_e32 v4, v173, v0
	s_addc_u32 s3, s11, s3
	v_div_scale_f32 v5, s[10:11], v4, v4, 1.0
	v_rcp_f32_e32 v6, v5
	v_lshlrev_b32_e32 v0, 3, v170
	v_lshl_add_u64 v[2:3], s[2:3], 0, v[0:1]
	s_mov_b64 s[2:3], 0x3d200000
	v_fma_f32 v0, -v5, v6, 1.0
	v_fmac_f32_e32 v6, v0, v6
	v_div_scale_f32 v0, vcc, 1.0, v4, 1.0
	v_lshl_add_u64 v[150:151], v[2:3], 0, s[2:3]
	v_mul_f32_e32 v2, v0, v6
	v_fma_f32 v3, -v5, v2, v0
	v_fmac_f32_e32 v2, v3, v6
	v_fma_f32 v0, -v5, v2, v0
	v_div_fmas_f32 v0, v0, v6, v2
	v_div_fixup_f32 v0, v0, v4, 1.0
	v_lshl_add_u64 v[4:5], v[152:153], 0, s[52:53]
	v_mul_f32_e32 v8, v34, v0
	v_mul_f32_e32 v9, v35, v0
	v_cvt_pk_bf16_f32 v204, v8, v9
	v_mul_f32_e32 v10, v36, v0
	v_mul_f32_e32 v11, v37, v0
	v_cvt_pk_bf16_f32 v205, v10, v11
	v_mul_f32_e32 v12, v18, v0
	v_mul_f32_e32 v13, v19, v0
	v_cvt_pk_bf16_f32 v212, v12, v13
	v_mul_f32_e32 v14, v20, v0
	v_mul_f32_e32 v15, v21, v0
	v_cvt_pk_bf16_f32 v213, v14, v15
	v_mbcnt_lo_u32_b32 v230, -1, 0
	v_mbcnt_hi_u32_b32 v230, -1, v230
	v_and_b32_e32 v230, 32, v230
	v_lshrrev_b32_e32 v230, 2, v230
	v_mov_b32_e32 v231, 0
	v_lshl_add_u64 v[228:229], v[4:5], 0, v[230:231]
	v_mul_f32_e32 v18, v38, v0
	v_mul_f32_e32 v19, v39, v0
	v_cvt_pk_bf16_f32 v206, v18, v19
	v_mul_f32_e32 v20, v40, v0
	v_mul_f32_e32 v21, v41, v0
	v_cvt_pk_bf16_f32 v207, v20, v21
	v_mul_f32_e32 v22, v22, v0
	v_mul_f32_e32 v23, v23, v0
	v_cvt_pk_bf16_f32 v214, v22, v23
	v_mul_f32_e32 v24, v24, v0
	v_mul_f32_e32 v25, v25, v0
	v_cvt_pk_bf16_f32 v215, v24, v25
	s_nop 1
	v_permlane32_swap_b32 v204, v206
	v_permlane32_swap_b32 v205, v207
	global_store_dwordx4 v[228:229], v[204:207], off
	s_nop 1
	v_permlane32_swap_b32 v212, v214
	v_permlane32_swap_b32 v213, v215
	global_store_dwordx4 v[228:229], v[212:215], off offset:64
	v_mul_f32_e32 v34, v42, v0
	v_mul_f32_e32 v35, v43, v0
	v_cvt_pk_bf16_f32 v208, v34, v35
	v_mul_f32_e32 v36, v44, v0
	v_mul_f32_e32 v37, v45, v0
	v_cvt_pk_bf16_f32 v209, v36, v37
	v_mul_f32_e32 v26, v26, v0
	v_mul_f32_e32 v27, v27, v0
	v_cvt_pk_bf16_f32 v216, v26, v27
	v_mul_f32_e32 v28, v28, v0
	v_mul_f32_e32 v29, v29, v0
	v_cvt_pk_bf16_f32 v217, v28, v29
	v_mul_f32_e32 v2, v46, v0
	v_mul_f32_e32 v3, v47, v0
	v_mul_f32_e32 v38, v48, v0
	v_mul_f32_e32 v39, v49, v0
	v_mul_f32_e32 v30, v30, v0
	v_mul_f32_e32 v31, v31, v0
	v_mul_f32_e32 v32, v32, v0
	v_mul_f32_e32 v33, v33, v0
	v_mul_f32_e32 v0, v12, v12
	v_fmac_f32_e32 v0, v8, v8
	v_mul_f32_e32 v8, v13, v13
	v_fmac_f32_e32 v8, v9, v9
	v_add_f32_e32 v0, v0, v8
	v_mul_f32_e32 v8, v14, v14
	v_fmac_f32_e32 v8, v10, v10
	v_add_f32_e32 v0, v8, v0
	v_mul_f32_e32 v8, v15, v15
	v_fmac_f32_e32 v8, v11, v11
	v_add_f32_e32 v0, v8, v0
	v_mul_f32_e32 v8, v22, v22
	v_fmac_f32_e32 v8, v18, v18
	v_add_f32_e32 v0, v8, v0
	v_mul_f32_e32 v8, v23, v23
	v_fmac_f32_e32 v8, v19, v19
	v_add_f32_e32 v0, v8, v0
	v_mul_f32_e32 v8, v24, v24
	v_fmac_f32_e32 v8, v20, v20
	v_add_f32_e32 v0, v8, v0
	v_mul_f32_e32 v8, v25, v25
	v_fmac_f32_e32 v8, v21, v21
	v_add_f32_e32 v0, v8, v0
	v_mul_f32_e32 v8, v26, v26
	v_fmac_f32_e32 v8, v34, v34
	v_add_f32_e32 v0, v8, v0
	v_mul_f32_e32 v8, v27, v27
	v_fmac_f32_e32 v8, v35, v35
	v_add_f32_e32 v0, v8, v0
	v_mul_f32_e32 v8, v28, v28
	v_fmac_f32_e32 v8, v36, v36
	v_add_f32_e32 v0, v8, v0
	v_mul_f32_e32 v8, v29, v29
	v_fmac_f32_e32 v8, v37, v37
	v_add_f32_e32 v0, v8, v0
	v_mul_f32_e32 v8, v30, v30
	v_cvt_pk_bf16_f32 v210, v2, v3
	v_fmac_f32_e32 v8, v2, v2
	v_mul_f32_e32 v2, v31, v31
	v_add_f32_e32 v0, v8, v0
	v_fmac_f32_e32 v2, v3, v3
	v_add_f32_e32 v0, v2, v0
	v_mul_f32_e32 v2, v32, v32
	v_fmac_f32_e32 v2, v38, v38
	v_add_f32_e32 v0, v2, v0
	v_mul_f32_e32 v2, v33, v33
	v_fmac_f32_e32 v2, v39, v39
	v_add_f32_e32 v0, v2, v0
	ds_bpermute_b32 v2, v17, v0
	v_cmp_gt_u32_e64 s[8:9], 32, v171
	v_cvt_pk_bf16_f32 v211, v38, v39
	v_cvt_pk_bf16_f32 v218, v30, v31
	v_cvt_pk_bf16_f32 v219, v32, v33
	s_nop 1
	v_permlane32_swap_b32 v208, v210
	v_permlane32_swap_b32 v209, v211
	global_store_dwordx4 v[228:229], v[208:211], off offset:32
	s_nop 1
	v_permlane32_swap_b32 v216, v218
	v_permlane32_swap_b32 v217, v219
	global_store_dwordx4 v[228:229], v[216:219], off offset:96
	s_and_saveexec_b64 s[2:3], s[8:9]
	s_cbranch_execz .LBB0_806
	s_waitcnt lgkmcnt(0)
	v_add_f32_e32 v0, v0, v2
	v_mul_f32_e32 v0, 0x4b800000, v0
	v_trunc_f32_e32 v0, v0
	v_mul_f32_e32 v2, 0x2f800000, v0
	v_floor_f32_e32 v3, v2
	v_fmac_f32_e32 v0, 0xcf800000, v3
	v_cvt_u32_f32_e32 v2, v0
	v_cvt_u32_f32_e32 v3, v3
	global_atomic_add_x2 v[150:151], v[2:3], off

; __device__ __forceinline__ unsigned cvtpk(float lo, float hi) { unsigned r; asm volatile("v_cvt_pk_bf16_f32 %0, %1, %2" : "=v"(r) : "v"(lo), "v"(hi)); return r; }
; __device__ __forceinline__ float shfl_x(float v, int m, int lane) { return __builtin_bit_cast(float, __builtin_amdgcn_ds_bpermute((lane ^ m) << 2, __builtin_bit_cast(int, v))); }
; __device__ __forceinline__ void swa_unit3(LAS unsigned char* lds, const bf16_t* pb  , bf16_t* Yb  , int q0, int kvh,
;                                           const float* sinks  , unsigned long long* gss, const int wave_s) {
;     ...
;         const float lt = l_run + shfl_x(l_run, 32, lane);
;         const float inv = 1.0f / lt;
;         bf16_t* orow = Yb + (size_t)(qw0 + r32) * DM + 64 * hq + 4 * hi;
; #pragma unroll
;         for (int rg = 0; rg < 4; ++rg) {
;             u32x2 a, b;
;             a.x = cvtpk(o0[4 * rg] * inv, o0[4 * rg + 1] * inv); a.y = cvtpk(o0[4 * rg + 2] * inv, o0[4 * rg + 3] * inv);
;             b.x = cvtpk(o1[4 * rg] * inv, o1[4 * rg + 1] * inv); b.y = cvtpk(o1[4 * rg + 2] * inv, o1[4 * rg + 3] * inv);
;             *(u32x2*)(orow + 8 * rg) = a; *(u32x2*)(orow + 32 + 8 * rg) = b;
;         }
;         { float q = 0.f;
; #pragma unroll
;           for (int r = 0; r < 16; ++r) { const float a = o0[r] * inv, b = o1[r] * inv; q += a * a + b * b; }
;           q += shfl_x(q, 32, lane);
;           if (hi == 0) __hip_atomic_fetch_add(gss + qw0 + r32, (unsigned long long)(q * 16777216.0f), __ATOMIC_RELAXED, __HIP_MEMORY_SCOPE_AGENT); }
.LBB0_816:
	ds_bpermute_b32 v0, v17, v154
	s_lshl_b32 s52, s25, 1
	s_waitcnt lgkmcnt(0)
	v_add_f32_e32 v0, v154, v0
	v_div_scale_f32 v2, s[2:3], v0, v0, 1.0
	v_rcp_f32_e32 v3, v2
	s_nop 0
	v_fma_f32 v4, -v2, v3, 1.0
	v_fmac_f32_e32 v3, v4, v3
	v_div_scale_f32 v4, vcc, 1.0, v0, 1.0
	v_mul_f32_e32 v5, v4, v3
	v_fma_f32 v6, -v2, v5, v4
	v_fmac_f32_e32 v5, v6, v3
	v_fma_f32 v2, -v2, v5, v4
	v_div_fmas_f32 v2, v2, v3, v5
	v_div_fixup_f32 v0, v2, v0, 1.0
	v_lshl_add_u64 v[2:3], v[152:153], 0, s[52:53]
	v_mul_f32_e32 v8, v34, v0
	v_mul_f32_e32 v9, v35, v0
	v_cvt_pk_bf16_f32 v204, v8, v9
	v_mul_f32_e32 v10, v36, v0
	v_mul_f32_e32 v11, v37, v0
	v_cvt_pk_bf16_f32 v205, v10, v11
	v_mul_f32_e32 v12, v18, v0
	v_mul_f32_e32 v13, v19, v0
	v_cvt_pk_bf16_f32 v212, v12, v13
	v_mul_f32_e32 v14, v20, v0
	v_mul_f32_e32 v15, v21, v0
	v_cvt_pk_bf16_f32 v213, v14, v15
	v_mbcnt_lo_u32_b32 v230, -1, 0
	v_mbcnt_hi_u32_b32 v230, -1, v230
	v_and_b32_e32 v230, 32, v230
	v_lshrrev_b32_e32 v230, 2, v230
	v_mov_b32_e32 v231, 0
	v_lshl_add_u64 v[228:229], v[2:3], 0, v[230:231]
	v_mul_f32_e32 v18, v38, v0
	v_mul_f32_e32 v19, v39, v0
	v_cvt_pk_bf16_f32 v206, v18, v19
	v_mul_f32_e32 v20, v40, v0
	v_mul_f32_e32 v21, v41, v0
	v_cvt_pk_bf16_f32 v207, v20, v21
	v_mul_f32_e32 v22, v22, v0
	v_mul_f32_e32 v23, v23, v0
	v_cvt_pk_bf16_f32 v214, v22, v23
	v_mul_f32_e32 v24, v24, v0
	v_mul_f32_e32 v25, v25, v0
	v_cvt_pk_bf16_f32 v215, v24, v25
	s_nop 1
	v_permlane32_swap_b32 v204, v206
	v_permlane32_swap_b32 v205, v207
	global_store_dwordx4 v[228:229], v[204:207], off
	s_nop 1
	v_permlane32_swap_b32 v212, v214
	v_permlane32_swap_b32 v213, v215
	global_store_dwordx4 v[228:229], v[212:215], off offset:64
	v_mul_f32_e32 v34, v42, v0
	v_mul_f32_e32 v35, v43, v0
	v_cvt_pk_bf16_f32 v208, v34, v35
	v_mul_f32_e32 v36, v44, v0
	v_mul_f32_e32 v37, v45, v0
	v_cvt_pk_bf16_f32 v209, v36, v37
	v_mul_f32_e32 v26, v26, v0
	v_mul_f32_e32 v27, v27, v0
	v_cvt_pk_bf16_f32 v216, v26, v27
	v_mul_f32_e32 v28, v28, v0
	v_mul_f32_e32 v29, v29, v0
	v_cvt_pk_bf16_f32 v217, v28, v29
	v_mul_f32_e32 v38, v46, v0
	v_mul_f32_e32 v39, v47, v0
	v_cvt_pk_bf16_f32 v210, v38, v39
	v_mul_f32_e32 v40, v48, v0
	v_mul_f32_e32 v41, v49, v0
	v_cvt_pk_bf16_f32 v211, v40, v41
	v_mul_f32_e32 v30, v30, v0
	v_mul_f32_e32 v31, v31, v0
	v_cvt_pk_bf16_f32 v218, v30, v31
	v_mul_f32_e32 v32, v32, v0
	v_mul_f32_e32 v0, v33, v0
	v_cvt_pk_bf16_f32 v219, v32, v0
	s_nop 1
	v_permlane32_swap_b32 v208, v210
	v_permlane32_swap_b32 v209, v211
	global_store_dwordx4 v[228:229], v[208:211], off offset:32
	s_nop 1
	v_permlane32_swap_b32 v216, v218
	v_permlane32_swap_b32 v217, v219
	global_store_dwordx4 v[228:229], v[216:219], off offset:96
	v_mul_f32_e32 v2, v12, v12
	v_mul_f32_e32 v3, v13, v13
	v_fmac_f32_e32 v2, v8, v8
	v_fmac_f32_e32 v3, v9, v9
	v_add_f32_e32 v2, v2, v3
	v_mul_f32_e32 v3, v14, v14
	v_fmac_f32_e32 v3, v10, v10
	v_add_f32_e32 v2, v3, v2
	v_mul_f32_e32 v3, v15, v15
	v_fmac_f32_e32 v3, v11, v11
	v_add_f32_e32 v2, v3, v2
	v_mul_f32_e32 v3, v22, v22
	v_fmac_f32_e32 v3, v18, v18
	v_add_f32_e32 v2, v3, v2
	v_mul_f32_e32 v3, v23, v23
	v_fmac_f32_e32 v3, v19, v19
	v_add_f32_e32 v2, v3, v2
	v_mul_f32_e32 v3, v24, v24
	v_fmac_f32_e32 v3, v20, v20
	v_add_f32_e32 v2, v3, v2
	v_mul_f32_e32 v3, v25, v25
	v_fmac_f32_e32 v3, v21, v21
	v_add_f32_e32 v2, v3, v2
	v_mul_f32_e32 v3, v26, v26
	v_fmac_f32_e32 v3, v34, v34
	v_add_f32_e32 v2, v3, v2
	v_mul_f32_e32 v3, v27, v27
	v_fmac_f32_e32 v3, v35, v35
	v_add_f32_e32 v2, v3, v2
	v_mul_f32_e32 v3, v28, v28
	v_fmac_f32_e32 v3, v36, v36
	v_add_f32_e32 v2, v3, v2
	v_mul_f32_e32 v3, v29, v29
	v_fmac_f32_e32 v3, v37, v37
	v_add_f32_e32 v2, v3, v2
	v_mul_f32_e32 v3, v30, v30
	v_fmac_f32_e32 v3, v38, v38
	v_add_f32_e32 v2, v3, v2
	v_mul_f32_e32 v3, v31, v31
	v_fmac_f32_e32 v3, v39, v39
	v_add_f32_e32 v2, v3, v2
	v_mul_f32_e32 v3, v32, v32
	v_fmac_f32_e32 v3, v40, v40
	v_mul_f32_e32 v0, v0, v0
	v_add_f32_e32 v2, v3, v2
	v_fmac_f32_e32 v0, v41, v41
	v_add_f32_e32 v0, v0, v2
	ds_bpermute_b32 v2, v17, v0
	s_and_saveexec_b64 s[2:3], s[8:9]
	s_cbranch_execz .LBB0_818
	s_waitcnt lgkmcnt(0)
	v_add_f32_e32 v0, v0, v2
	v_mul_f32_e32 v0, 0x4b800000, v0
	v_trunc_f32_e32 v0, v0
	v_mul_f32_e32 v2, 0x2f800000, v0
	v_floor_f32_e32 v3, v2
	v_fmac_f32_e32 v0, 0xcf800000, v3
	v_cvt_u32_f32_e32 v2, v0
	v_cvt_u32_f32_e32 v3, v3
	global_atomic_add_x2 v[150:151], v[2:3], off

; __device__ __forceinline__ unsigned cvtpk(float lo, float hi) { unsigned r; asm volatile("v_cvt_pk_bf16_f32 %0, %1, %2" : "=v"(r) : "v"(lo), "v"(hi)); return r; }
; __device__ __forceinline__ float shfl_x(float v, int m, int lane) { return __builtin_bit_cast(float, __builtin_amdgcn_ds_bpermute((lane ^ m) << 2, __builtin_bit_cast(int, v))); }
; __device__ __forceinline__ void swa_unit3(LAS unsigned char* lds, const bf16_t* pb  , bf16_t* Yb  , int q0, int kvh,
;                                           const float* sinks  , unsigned long long* gss, const int wave_s) {
;     ...
;         const float lt = l_run + shfl_x(l_run, 32, lane);
;         const float inv = 1.0f / lt;
;         bf16_t* orow = Yb + (size_t)(qw0 + r32) * DM + 64 * hq + 4 * hi;
; #pragma unroll
;         for (int rg = 0; rg < 4; ++rg) {
;             u32x2 a, b;
;             a.x = cvtpk(o0[4 * rg] * inv, o0[4 * rg + 1] * inv); a.y = cvtpk(o0[4 * rg + 2] * inv, o0[4 * rg + 3] * inv);
;             b.x = cvtpk(o1[4 * rg] * inv, o1[4 * rg + 1] * inv); b.y = cvtpk(o1[4 * rg + 2] * inv, o1[4 * rg + 3] * inv);
;             *(u32x2*)(orow + 8 * rg) = a; *(u32x2*)(orow + 32 + 8 * rg) = b;
;         }
;         { float q = 0.f;
; #pragma unroll
;           for (int r = 0; r < 16; ++r) { const float a = o0[r] * inv, b = o1[r] * inv; q += a * a + b * b; }
;           q += shfl_x(q, 32, lane);
;           if (hi == 0) __hip_atomic_fetch_add(gss + qw0 + r32, (unsigned long long)(q * 16777216.0f), __ATOMIC_RELAXED, __HIP_MEMORY_SCOPE_AGENT); }
.LBB0_828:
	ds_bpermute_b32 v0, v17, v134
	s_lshl_b32 s52, s24, 1
	v_lshl_add_u64 v[4:5], v[152:153], 0, s[52:53]
	s_waitcnt lgkmcnt(0)
	v_add_f32_e32 v0, v134, v0
	v_div_scale_f32 v2, s[2:3], v0, v0, 1.0
	v_rcp_f32_e32 v3, v2
	v_div_scale_f32 v6, vcc, 1.0, v0, 1.0
	v_fma_f32 v7, -v2, v3, 1.0
	v_fmac_f32_e32 v3, v7, v3
	v_mul_f32_e32 v7, v6, v3
	v_fma_f32 v8, -v2, v7, v6
	v_fmac_f32_e32 v7, v8, v3
	v_fma_f32 v2, -v2, v7, v6
	v_div_fmas_f32 v2, v2, v3, v7
	v_div_fixup_f32 v0, v2, v0, 1.0
	v_mul_f32_e32 v8, v34, v0
	v_mul_f32_e32 v9, v35, v0
	v_cvt_pk_bf16_f32 v204, v8, v9
	v_mul_f32_e32 v10, v36, v0
	v_mul_f32_e32 v11, v37, v0
	v_cvt_pk_bf16_f32 v205, v10, v11
	v_mul_f32_e32 v12, v18, v0
	v_mul_f32_e32 v13, v19, v0
	v_cvt_pk_bf16_f32 v212, v12, v13
	v_mul_f32_e32 v14, v20, v0
	v_mul_f32_e32 v15, v21, v0
	v_cvt_pk_bf16_f32 v213, v14, v15
	v_mbcnt_lo_u32_b32 v230, -1, 0
	v_mbcnt_hi_u32_b32 v230, -1, v230
	v_and_b32_e32 v230, 32, v230
	v_lshrrev_b32_e32 v230, 2, v230
	v_mov_b32_e32 v231, 0
	v_lshl_add_u64 v[228:229], v[4:5], 0, v[230:231]
	v_mul_f32_e32 v18, v38, v0
	v_mul_f32_e32 v19, v39, v0
	v_cvt_pk_bf16_f32 v206, v18, v19
	v_mul_f32_e32 v20, v40, v0
	v_mul_f32_e32 v21, v41, v0
	v_cvt_pk_bf16_f32 v207, v20, v21
	v_mul_f32_e32 v22, v22, v0
	v_mul_f32_e32 v23, v23, v0
	v_cvt_pk_bf16_f32 v214, v22, v23
	v_mul_f32_e32 v24, v24, v0
	v_mul_f32_e32 v25, v25, v0
	v_cvt_pk_bf16_f32 v215, v24, v25
	s_nop 1
	v_permlane32_swap_b32 v204, v206
	v_permlane32_swap_b32 v205, v207
	global_store_dwordx4 v[228:229], v[204:207], off
	s_nop 1
	v_permlane32_swap_b32 v212, v214
	v_permlane32_swap_b32 v213, v215
	global_store_dwordx4 v[228:229], v[212:215], off offset:64
	v_mul_f32_e32 v34, v42, v0
	v_mul_f32_e32 v35, v43, v0
	v_cvt_pk_bf16_f32 v208, v34, v35
	v_mul_f32_e32 v36, v44, v0
	v_mul_f32_e32 v37, v45, v0
	v_cvt_pk_bf16_f32 v209, v36, v37
	v_mul_f32_e32 v26, v26, v0
	v_mul_f32_e32 v27, v27, v0
	v_cvt_pk_bf16_f32 v216, v26, v27
	v_mul_f32_e32 v28, v28, v0
	v_mul_f32_e32 v29, v29, v0
	v_cvt_pk_bf16_f32 v217, v28, v29
	v_mul_f32_e32 v2, v46, v0
	v_mul_f32_e32 v3, v47, v0
	v_mul_f32_e32 v38, v48, v0
	v_mul_f32_e32 v39, v49, v0
	v_mul_f32_e32 v30, v30, v0
	v_mul_f32_e32 v31, v31, v0
	v_mul_f32_e32 v32, v32, v0
	v_mul_f32_e32 v33, v33, v0
	v_mul_f32_e32 v0, v12, v12
	v_fmac_f32_e32 v0, v8, v8
	v_mul_f32_e32 v8, v13, v13
	v_fmac_f32_e32 v8, v9, v9
	v_add_f32_e32 v0, v0, v8
	v_mul_f32_e32 v8, v14, v14
	v_fmac_f32_e32 v8, v10, v10
	v_add_f32_e32 v0, v8, v0
	v_mul_f32_e32 v8, v15, v15
	v_fmac_f32_e32 v8, v11, v11
	v_add_f32_e32 v0, v8, v0
	v_mul_f32_e32 v8, v22, v22
	v_fmac_f32_e32 v8, v18, v18
	v_add_f32_e32 v0, v8, v0
	v_mul_f32_e32 v8, v23, v23
	v_fmac_f32_e32 v8, v19, v19
	v_add_f32_e32 v0, v8, v0
	v_mul_f32_e32 v8, v24, v24
	v_fmac_f32_e32 v8, v20, v20
	v_add_f32_e32 v0, v8, v0
	v_mul_f32_e32 v8, v25, v25
	v_fmac_f32_e32 v8, v21, v21
	v_add_f32_e32 v0, v8, v0
	v_mul_f32_e32 v8, v26, v26
	v_fmac_f32_e32 v8, v34, v34
	v_add_f32_e32 v0, v8, v0
	v_mul_f32_e32 v8, v27, v27
	v_fmac_f32_e32 v8, v35, v35
	v_add_f32_e32 v0, v8, v0
	v_mul_f32_e32 v8, v28, v28
	v_fmac_f32_e32 v8, v36, v36
	v_add_f32_e32 v0, v8, v0
	v_mul_f32_e32 v8, v29, v29
	v_fmac_f32_e32 v8, v37, v37
	v_add_f32_e32 v0, v8, v0
	v_mul_f32_e32 v8, v30, v30
	v_cvt_pk_bf16_f32 v210, v2, v3
	v_fmac_f32_e32 v8, v2, v2
	v_mul_f32_e32 v2, v31, v31
	v_add_f32_e32 v0, v8, v0
	v_fmac_f32_e32 v2, v3, v3
	v_add_f32_e32 v0, v2, v0
	v_mul_f32_e32 v2, v32, v32
	v_fmac_f32_e32 v2, v38, v38
	v_add_f32_e32 v0, v2, v0
	v_mul_f32_e32 v2, v33, v33
	v_fmac_f32_e32 v2, v39, v39
	v_add_f32_e32 v0, v2, v0
	ds_bpermute_b32 v2, v17, v0
	v_cvt_pk_bf16_f32 v211, v38, v39
	v_cvt_pk_bf16_f32 v218, v30, v31
	v_cvt_pk_bf16_f32 v219, v32, v33
	s_nop 1
	v_permlane32_swap_b32 v208, v210
	v_permlane32_swap_b32 v209, v211
	global_store_dwordx4 v[228:229], v[208:211], off offset:32
	s_nop 1
	v_permlane32_swap_b32 v216, v218
	v_permlane32_swap_b32 v217, v219
	global_store_dwordx4 v[228:229], v[216:219], off offset:96
	s_and_saveexec_b64 s[2:3], s[8:9]
	s_cbranch_execz .LBB0_769
	s_waitcnt lgkmcnt(0)
	v_add_f32_e32 v0, v0, v2
	v_mul_f32_e32 v0, 0x4b800000, v0
	v_trunc_f32_e32 v0, v0
	v_mul_f32_e32 v2, 0x2f800000, v0
	v_floor_f32_e32 v3, v2
	v_fmac_f32_e32 v0, 0xcf800000, v3
	v_cvt_u32_f32_e32 v2, v0
	v_cvt_u32_f32_e32 v3, v3
	global_atomic_add_x2 v[150:151], v[2:3], off
	s_branch .LBB0_769

; __device__ __forceinline__ unsigned cvtpk(float lo, float hi) { unsigned r; asm volatile("v_cvt_pk_bf16_f32 %0, %1, %2" : "=v"(r) : "v"(lo), "v"(hi)); return r; }
; __device__ __forceinline__ float shfl_x(float v, int m, int lane) { return __builtin_bit_cast(float, __builtin_amdgcn_ds_bpermute((lane ^ m) << 2, __builtin_bit_cast(int, v))); }
; template <int NDS, int MODE> ...
;     ...
;     const float lt = l_run + shfl_x(l_run, 32, lane);
;     const float inv = 1.0f / lt;
;     bf16_t* orow = O + (size_t)(qw0 + r32) * op + 4 * hi;
; #pragma unroll
;     for (int rg = 0; rg < 4; ++rg) {
;         u32x2 a, b;
;         a.x = cvtpk(o0[4 * rg] * inv, o0[4 * rg + 1] * inv); a.y = cvtpk(o0[4 * rg + 2] * inv, o0[4 * rg + 3] * inv);
;         b.x = cvtpk(o1[4 * rg] * inv, o1[4 * rg + 1] * inv); b.y = cvtpk(o1[4 * rg + 2] * inv, o1[4 * rg + 3] * inv);
;         *(u32x2*)(orow + 8 * rg) = a; *(u32x2*)(orow + 32 + 8 * rg) = b;
;     }
;     { float q = 0.f;
; #pragma unroll
;       for (int r = 0; r < 16; ++r) { const float a = o0[r] * inv, b = o1[r] * inv; q += a * a + b * b; }
;       q += shfl_x(q, 32, lane);
;       if (hi == 0) __hip_atomic_fetch_add(gss + qw0 + r32, (unsigned long long)(q * 16777216.0f), __ATOMIC_RELAXED, __HIP_MEMORY_SCOPE_AGENT); }
.LBB0_959:
	ds_bpermute_b32 v0, v194, v14
	s_lshl_b64 s[12:13], s[34:35], 12
	s_lshl_b64 s[2:3], s[34:35], 23
	s_add_u32 s4, s28, s2
	s_addc_u32 s6, s29, s3
	s_lshl_b32 s2, s31, 6
	s_ashr_i32 s3, s2, 31
	s_lshl_b64 s[2:3], s[2:3], 1
	s_waitcnt lgkmcnt(0)
	v_add_f32_e32 v0, v14, v0
	s_add_u32 s2, s4, s2
	v_div_scale_f32 v2, s[4:5], v0, v0, 1.0
	v_rcp_f32_e32 v3, v2
	s_addc_u32 s3, s6, s3
	s_add_u32 s28, s2, 0x2c800300
	s_addc_u32 s29, s3, 0
	v_fma_f32 v4, -v2, v3, 1.0
	v_fmac_f32_e32 v3, v4, v3
	v_div_scale_f32 v4, vcc, 1.0, v0, 1.0
	v_mul_f32_e32 v5, v4, v3
	v_fma_f32 v6, -v2, v5, v4
	v_fmac_f32_e32 v5, v6, v3
	v_fma_f32 v2, -v2, v5, v4
	v_div_fmas_f32 v2, v2, v3, v5
	v_div_fixup_f32 v9, v2, v0, 1.0
	v_lshlrev_b64 v[2:3], 11, v[168:169]
	v_lshl_add_u64 v[2:3], s[28:29], 0, v[2:3]
	v_lshlrev_b32_e32 v0, 1, v197
	v_mul_f32_e32 v13, v32, v9
	v_lshl_add_u64 v[4:5], v[2:3], 0, v[0:1]
	v_mul_f32_e32 v0, v48, v9
	v_mul_f32_e32 v10, v49, v9
	v_cvt_pk_bf16_f32 v204, v0, v10
	v_mul_f32_e32 v11, v50, v9
	v_mul_f32_e32 v12, v51, v9
	v_cvt_pk_bf16_f32 v205, v11, v12
	v_mul_f32_e32 v14, v33, v9
	v_cvt_pk_bf16_f32 v212, v13, v14
	v_mul_f32_e32 v13, v13, v13
	v_mul_f32_e32 v15, v34, v9
	v_fmac_f32_e32 v13, v0, v0
	v_mul_f32_e32 v0, v14, v14
	v_fmac_f32_e32 v0, v10, v10
	v_mul_f32_e32 v10, v15, v15
	v_mul_f32_e32 v17, v35, v9
	v_add_f32_e32 v0, v13, v0
	v_fmac_f32_e32 v10, v11, v11
	v_add_f32_e32 v0, v10, v0
	v_mul_f32_e32 v10, v17, v17
	v_mul_f32_e32 v22, v36, v9
	v_fmac_f32_e32 v10, v12, v12
	v_mul_f32_e32 v18, v52, v9
	v_add_f32_e32 v0, v10, v0
	v_mul_f32_e32 v10, v22, v22
	v_mul_f32_e32 v23, v37, v9
	v_fmac_f32_e32 v10, v18, v18
	v_mul_f32_e32 v19, v53, v9
	v_add_f32_e32 v0, v10, v0
	v_mul_f32_e32 v10, v23, v23
	v_mul_f32_e32 v24, v38, v9
	v_fmac_f32_e32 v10, v19, v19
	v_mul_f32_e32 v20, v54, v9
	v_add_f32_e32 v0, v10, v0
	v_mul_f32_e32 v10, v24, v24
	v_mul_f32_e32 v25, v39, v9
	v_fmac_f32_e32 v10, v20, v20
	v_mul_f32_e32 v21, v55, v9
	v_add_f32_e32 v0, v10, v0
	v_mul_f32_e32 v10, v25, v25
	v_mul_f32_e32 v30, v40, v9
	v_fmac_f32_e32 v10, v21, v21
	v_mul_f32_e32 v26, v56, v9
	v_add_f32_e32 v0, v10, v0
	v_mul_f32_e32 v10, v30, v30
	v_mul_f32_e32 v31, v41, v9
	v_fmac_f32_e32 v10, v26, v26
	v_mul_f32_e32 v27, v57, v9
	v_add_f32_e32 v0, v10, v0
	v_mul_f32_e32 v10, v31, v31
	v_mul_f32_e32 v32, v42, v9
	v_fmac_f32_e32 v10, v27, v27
	v_mul_f32_e32 v28, v58, v9
	v_add_f32_e32 v0, v10, v0
	v_mul_f32_e32 v10, v32, v32
	v_mul_f32_e32 v33, v43, v9
	v_fmac_f32_e32 v10, v28, v28
	v_cvt_pk_bf16_f32 v213, v15, v17
	v_mbcnt_lo_u32_b32 v230, -1, 0
	v_mbcnt_hi_u32_b32 v230, -1, v230
	v_and_b32_e32 v230, 32, v230
	v_lshrrev_b32_e32 v230, 2, v230
	v_mov_b32_e32 v231, 0
	v_lshl_add_u64 v[228:229], v[4:5], 0, v[230:231]
	v_cvt_pk_bf16_f32 v206, v18, v19
	v_cvt_pk_bf16_f32 v207, v20, v21
	v_mul_f32_e32 v29, v59, v9
	v_add_f32_e32 v0, v10, v0
	v_mul_f32_e32 v10, v33, v33
	v_cvt_pk_bf16_f32 v214, v22, v23
	v_cvt_pk_bf16_f32 v215, v24, v25
	s_nop 1
	v_permlane32_swap_b32 v204, v206
	v_permlane32_swap_b32 v205, v207
	global_store_dwordx4 v[228:229], v[204:207], off
	s_nop 1
	v_permlane32_swap_b32 v212, v214
	v_permlane32_swap_b32 v213, v215
	global_store_dwordx4 v[228:229], v[212:215], off offset:64
	v_cvt_pk_bf16_f32 v208, v26, v27
	v_cvt_pk_bf16_f32 v209, v28, v29
	v_mul_f32_e32 v36, v44, v9
	v_fmac_f32_e32 v10, v29, v29
	v_cvt_pk_bf16_f32 v216, v30, v31
	v_cvt_pk_bf16_f32 v217, v32, v33
	v_mul_f32_e32 v2, v60, v9
	v_mul_f32_e32 v37, v45, v9
	v_add_f32_e32 v0, v10, v0
	v_mul_f32_e32 v10, v36, v36
	v_mul_f32_e32 v3, v61, v9
	v_cvt_pk_bf16_f32 v210, v2, v3
	v_fmac_f32_e32 v10, v2, v2
	v_mul_f32_e32 v2, v37, v37
	v_mul_f32_e32 v38, v46, v9
	v_add_f32_e32 v0, v10, v0
	v_fmac_f32_e32 v2, v3, v3
	v_mul_f32_e32 v34, v62, v9
	v_add_f32_e32 v0, v2, v0
	v_mul_f32_e32 v2, v38, v38
	v_mul_f32_e32 v35, v63, v9
	v_mul_f32_e32 v9, v47, v9
	v_fmac_f32_e32 v2, v34, v34
	v_add_f32_e32 v0, v2, v0
	v_mul_f32_e32 v2, v9, v9
	v_fmac_f32_e32 v2, v35, v35
	v_add_f32_e32 v2, v2, v0
	ds_bpermute_b32 v3, v194, v2
	v_cvt_pk_bf16_f32 v211, v34, v35
	v_cmp_gt_u32_e32 vcc, 32, v177
	v_cvt_pk_bf16_f32 v218, v36, v37
	v_cvt_pk_bf16_f32 v219, v38, v9
	s_nop 1
	v_permlane32_swap_b32 v208, v210
	v_permlane32_swap_b32 v209, v211
	global_store_dwordx4 v[228:229], v[208:211], off offset:32
	s_nop 1
	v_permlane32_swap_b32 v216, v218
	v_permlane32_swap_b32 v217, v219
	global_store_dwordx4 v[228:229], v[216:219], off offset:96
	s_and_saveexec_b64 s[2:3], vcc
	s_cbranch_execz .LBB0_961
	s_add_u32 s6, s22, s94
	s_addc_u32 s7, s23, s95
	s_lshl_b64 s[4:5], s[12:13], 3
	s_add_u32 s6, s6, s4
	s_addc_u32 s7, s7, s5
	s_ashr_i32 s31, s30, 31
	s_lshl_b64 s[4:5], s[30:31], 3
	s_add_u32 s4, s6, s4
	s_addc_u32 s5, s7, s5
	v_lshlrev_b32_e32 v0, 3, v176
	v_lshl_add_u64 v[4:5], s[4:5], 0, v[0:1]
	s_waitcnt lgkmcnt(0)
	v_add_f32_e32 v0, v2, v3
	v_mul_f32_e32 v0, 0x4b800000, v0
	v_trunc_f32_e32 v0, v0
	v_mul_f32_e32 v2, 0x2f800000, v0
	v_floor_f32_e32 v3, v2
	v_fmac_f32_e32 v0, 0xcf800000, v3
	v_cvt_u32_f32_e32 v2, v0
	v_cvt_u32_f32_e32 v3, v3
	v_add_co_u32_e32 v4, vcc, 0x3d280000, v4
	s_nop 1
	v_addc_co_u32_e32 v5, vcc, 0, v5, vcc
	global_atomic_add_x2 v[4:5], v[2:3], off

; __device__ __forceinline__ unsigned cvtpk(float lo, float hi) { unsigned r; asm volatile("v_cvt_pk_bf16_f32 %0, %1, %2" : "=v"(r) : "v"(lo), "v"(hi)); return r; }
; __device__ __forceinline__ float shfl_x(float v, int m, int lane) { return __builtin_bit_cast(float, __builtin_amdgcn_ds_bpermute((lane ^ m) << 2, __builtin_bit_cast(int, v))); }
; template <int NDS, int MODE> ...
;     ...
;     const float lt = l_run + shfl_x(l_run, 32, lane);
;     const float inv = 1.0f / lt;
;     bf16_t* orow = O + (size_t)(qw0 + r32) * op + 4 * hi;
; #pragma unroll
;     for (int rg = 0; rg < 4; ++rg) {
;         u32x2 a, b;
;         a.x = cvtpk(o0[4 * rg] * inv, o0[4 * rg + 1] * inv); a.y = cvtpk(o0[4 * rg + 2] * inv, o0[4 * rg + 3] * inv);
;         b.x = cvtpk(o1[4 * rg] * inv, o1[4 * rg + 1] * inv); b.y = cvtpk(o1[4 * rg + 2] * inv, o1[4 * rg + 3] * inv);
;         *(u32x2*)(orow + 8 * rg) = a; *(u32x2*)(orow + 32 + 8 * rg) = b;
;     }
;     { float q = 0.f;
; #pragma unroll
;       for (int r = 0; r < 16; ++r) { const float a = o0[r] * inv, b = o1[r] * inv; q += a * a + b * b; }
;       q += shfl_x(q, 32, lane);
;       if (hi == 0) __hip_atomic_fetch_add(gss + qw0 + r32, (unsigned long long)(q * 16777216.0f), __ATOMIC_RELAXED, __HIP_MEMORY_SCOPE_AGENT); }
.LBB0_1009:
	ds_bpermute_b32 v4, v174, v197
	v_lshlrev_b64 v[2:3], 11, v[14:15]
	v_lshlrev_b32_e32 v0, 1, v177
	v_lshl_add_u64 v[2:3], s[28:29], 0, v[2:3]
	s_waitcnt lgkmcnt(0)
	v_add_f32_e32 v4, v197, v4
	v_div_scale_f32 v5, s[2:3], v4, v4, 1.0
	v_rcp_f32_e32 v6, v5
	v_div_scale_f32 v7, vcc, 1.0, v4, 1.0
	v_fma_f32 v8, -v5, v6, 1.0
	v_fmac_f32_e32 v6, v8, v6
	v_mul_f32_e32 v8, v7, v6
	v_fma_f32 v9, -v5, v8, v7
	v_fmac_f32_e32 v8, v9, v6
	v_fma_f32 v5, -v5, v8, v7
	v_div_fmas_f32 v5, v5, v6, v8
	v_div_fixup_f32 v9, v5, v4, 1.0
	v_mul_f32_e32 v13, v48, v9
	v_lshl_add_u64 v[4:5], v[2:3], 0, v[0:1]
	v_mul_f32_e32 v0, v32, v9
	v_mul_f32_e32 v10, v33, v9
	v_cvt_pk_bf16_f32 v204, v0, v10
	v_mul_f32_e32 v11, v34, v9
	v_mul_f32_e32 v12, v35, v9
	v_cvt_pk_bf16_f32 v205, v11, v12
	v_mul_f32_e32 v14, v49, v9
	v_cvt_pk_bf16_f32 v212, v13, v14
	v_mul_f32_e32 v13, v13, v13
	v_mul_f32_e32 v15, v50, v9
	v_fmac_f32_e32 v13, v0, v0
	v_mul_f32_e32 v0, v14, v14
	v_fmac_f32_e32 v0, v10, v10
	v_mul_f32_e32 v10, v15, v15
	v_mul_f32_e32 v17, v51, v9
	v_add_f32_e32 v0, v13, v0
	v_fmac_f32_e32 v10, v11, v11
	v_add_f32_e32 v0, v10, v0
	v_mul_f32_e32 v10, v17, v17
	v_mul_f32_e32 v22, v52, v9
	v_fmac_f32_e32 v10, v12, v12
	v_mul_f32_e32 v18, v36, v9
	v_add_f32_e32 v0, v10, v0
	v_mul_f32_e32 v10, v22, v22
	v_mul_f32_e32 v23, v53, v9
	v_fmac_f32_e32 v10, v18, v18
	v_mul_f32_e32 v19, v37, v9
	v_add_f32_e32 v0, v10, v0
	v_mul_f32_e32 v10, v23, v23
	v_mul_f32_e32 v24, v54, v9
	v_fmac_f32_e32 v10, v19, v19
	v_mul_f32_e32 v20, v38, v9
	v_add_f32_e32 v0, v10, v0
	v_mul_f32_e32 v10, v24, v24
	v_mul_f32_e32 v25, v55, v9
	v_fmac_f32_e32 v10, v20, v20
	v_mul_f32_e32 v21, v39, v9
	v_add_f32_e32 v0, v10, v0
	v_mul_f32_e32 v10, v25, v25
	v_mul_f32_e32 v30, v56, v9
	v_fmac_f32_e32 v10, v21, v21
	v_mul_f32_e32 v26, v40, v9
	v_add_f32_e32 v0, v10, v0
	v_mul_f32_e32 v10, v30, v30
	v_mul_f32_e32 v31, v57, v9
	v_fmac_f32_e32 v10, v26, v26
	v_mul_f32_e32 v27, v41, v9
	v_add_f32_e32 v0, v10, v0
	v_mul_f32_e32 v10, v31, v31
	v_mul_f32_e32 v32, v58, v9
	v_fmac_f32_e32 v10, v27, v27
	v_mul_f32_e32 v28, v42, v9
	v_add_f32_e32 v0, v10, v0
	v_mul_f32_e32 v10, v32, v32
	v_mul_f32_e32 v33, v59, v9
	v_fmac_f32_e32 v10, v28, v28
	v_cvt_pk_bf16_f32 v213, v15, v17
	v_mbcnt_lo_u32_b32 v230, -1, 0
	v_mbcnt_hi_u32_b32 v230, -1, v230
	v_and_b32_e32 v230, 32, v230
	v_lshrrev_b32_e32 v230, 2, v230
	v_mov_b32_e32 v231, 0
	v_lshl_add_u64 v[228:229], v[4:5], 0, v[230:231]
	v_cvt_pk_bf16_f32 v206, v18, v19
	v_cvt_pk_bf16_f32 v207, v20, v21
	v_mul_f32_e32 v29, v43, v9
	v_add_f32_e32 v0, v10, v0
	v_mul_f32_e32 v10, v33, v33
	v_cvt_pk_bf16_f32 v214, v22, v23
	v_cvt_pk_bf16_f32 v215, v24, v25
	s_nop 1
	v_permlane32_swap_b32 v204, v206
	v_permlane32_swap_b32 v205, v207
	global_store_dwordx4 v[228:229], v[204:207], off
	s_nop 1
	v_permlane32_swap_b32 v212, v214
	v_permlane32_swap_b32 v213, v215
	global_store_dwordx4 v[228:229], v[212:215], off offset:64
	v_cvt_pk_bf16_f32 v208, v26, v27
	v_cvt_pk_bf16_f32 v209, v28, v29
	v_mul_f32_e32 v36, v60, v9
	v_fmac_f32_e32 v10, v29, v29
	v_cvt_pk_bf16_f32 v216, v30, v31
	v_cvt_pk_bf16_f32 v217, v32, v33
	v_mul_f32_e32 v2, v44, v9
	v_mul_f32_e32 v37, v61, v9
	v_add_f32_e32 v0, v10, v0
	v_mul_f32_e32 v10, v36, v36
	v_mul_f32_e32 v3, v45, v9
	v_cvt_pk_bf16_f32 v210, v2, v3
	v_fmac_f32_e32 v10, v2, v2
	v_mul_f32_e32 v2, v37, v37
	v_mul_f32_e32 v38, v62, v9
	v_add_f32_e32 v0, v10, v0
	v_fmac_f32_e32 v2, v3, v3
	v_mul_f32_e32 v34, v46, v9
	v_add_f32_e32 v0, v2, v0
	v_mul_f32_e32 v2, v38, v38
	v_mul_f32_e32 v35, v47, v9
	v_mul_f32_e32 v9, v63, v9
	v_fmac_f32_e32 v2, v34, v34
	v_add_f32_e32 v0, v2, v0
	v_mul_f32_e32 v2, v9, v9
	v_fmac_f32_e32 v2, v35, v35
	v_add_f32_e32 v2, v2, v0
	ds_bpermute_b32 v3, v174, v2
	v_cvt_pk_bf16_f32 v211, v34, v35
	v_cmp_gt_u32_e32 vcc, 32, v173
	v_cvt_pk_bf16_f32 v218, v36, v37
	v_cvt_pk_bf16_f32 v219, v38, v9
	s_nop 1
	v_permlane32_swap_b32 v208, v210
	v_permlane32_swap_b32 v209, v211
	global_store_dwordx4 v[228:229], v[208:211], off offset:32
	s_nop 1
	v_permlane32_swap_b32 v216, v218
	v_permlane32_swap_b32 v217, v219
	global_store_dwordx4 v[228:229], v[216:219], off offset:96
	s_and_saveexec_b64 s[2:3], vcc
	s_cbranch_execz .LBB0_909
	s_add_u32 s6, s22, s94
	s_addc_u32 s7, s23, s95
	s_lshl_b64 s[4:5], s[12:13], 3
	s_add_u32 s6, s6, s4
	s_addc_u32 s7, s7, s5
	s_ashr_i32 s31, s30, 31
	s_lshl_b64 s[4:5], s[30:31], 3
	s_add_u32 s4, s6, s4
	s_addc_u32 s5, s7, s5
	v_lshlrev_b32_e32 v0, 3, v172
	v_lshl_add_u64 v[4:5], s[4:5], 0, v[0:1]
	s_waitcnt lgkmcnt(0)
	v_add_f32_e32 v0, v2, v3
	v_mul_f32_e32 v0, 0x4b800000, v0
	v_trunc_f32_e32 v0, v0
	v_mul_f32_e32 v2, 0x2f800000, v0
	v_floor_f32_e32 v3, v2
	v_fmac_f32_e32 v0, 0xcf800000, v3
	v_cvt_u32_f32_e32 v2, v0
	v_cvt_u32_f32_e32 v3, v3
	v_add_co_u32_e32 v4, vcc, 0x3d280000, v4
	s_nop 1
	v_addc_co_u32_e32 v5, vcc, 0, v5, vcc
	global_atomic_add_x2 v[4:5], v[2:3], off
	s_branch .LBB0_909
